# grid barrier flat release: all workgroups spin on the cross-XCD generation word (two fewer dependent round trips per barrier)
# speedup vs baseline: 1.0578x; 1.0042x over previous
.Lcgx_267:
	s_or_b64 exec, exec, s[12:13]
	v_cvt_f32_u32_e32 v4, v2
	s_waitcnt vmcnt(0)
	v_readfirstlane_b32 s3, v3
	v_sub_u32_e32 v3, 0, v2
	v_rcp_iflag_f32_e32 v4, v4
	v_add_u32_e32 v5, s3, v1
	v_mul_f32_e32 v4, 0x4f7ffffe, v4
	v_cvt_u32_f32_e32 v4, v4
	v_mul_lo_u32 v1, v3, v4
	v_mul_hi_u32 v1, v4, v1
	v_add_u32_e32 v1, v4, v1
	v_mul_hi_u32 v1, v5, v1
	v_mul_lo_u32 v3, v1, v2
	v_sub_u32_e32 v3, v5, v3
	v_add_u32_e32 v4, 1, v1
	v_cmp_ge_u32_e32 vcc, v3, v2
	s_nop 1
	v_cndmask_b32_e32 v1, v1, v4, vcc
	v_sub_u32_e32 v4, v3, v2
	v_cndmask_b32_e32 v3, v3, v4, vcc
	v_add_u32_e32 v4, 1, v1
	v_cmp_ge_u32_e32 vcc, v3, v2
	v_add_u32_e32 v3, 1, v5
	s_nop 0
	v_cndmask_b32_e32 v1, v1, v4, vcc
	v_mul_lo_u32 v4, v2, v1
	v_add_u32_e32 v2, v4, v2
	v_cmp_ne_u32_e32 vcc, v3, v2
	s_and_saveexec_b64 s[10:11], vcc
	s_xor_b64 s[10:11], exec, s[10:11]
	s_cbranch_execz .Lcgx_281
	s_waitcnt lgkmcnt(0)
	v_mov_b32_e32 v0, 0x7500
	global_load_dword v0, v0, s[6:7] sc1
	s_add_u32 s16, s6, 0x7500
	s_addc_u32 s17, s7, 0
	s_waitcnt vmcnt(0)
	v_cmp_eq_u32_e32 vcc, v0, v1
	s_and_saveexec_b64 s[12:13], vcc
	s_cbranch_execz .Lcgx_280
	s_add_u32 s14, s6, 0x4200
	s_addc_u32 s15, s7, 0
	s_mov_b32 s3, 1
	s_mov_b64 s[18:19], 0
	v_mov_b32_e32 v0, 0
	s_branch .Lcgx_271
